# P2 and P9 k-loops: first iteration peeled with src C = 0, accumulator zeroing (128 v_mov per unit) removed
# speedup vs baseline: 1.0058x; 1.0033x over previous
;     __device__ __forceinline__ bool next(int i, Unit& u) const { return decode(i * G + c, u); }
; #define PG8_STAGE(bufoff, gbase, voff) do { _Pragma("unroll") for (int _i = 0; _i < 2; ++_i) \
;         __builtin_amdgcn_global_load_lds((const unsigned*)((const char*)(gbase) + (voff)[_i]), (LAS unsigned*)(lds + (bufoff) + ldsw + _i * 8192), 16, 0, 0); } while (0)
; #define PG8_LDA(dst, b, h) do { _Pragma("unroll") for (int m = 0; m < 4; ++m) _Pragma("unroll") for (int k = 0; k < 2; ++k) dst[m][k] = *(const LAS bf16x8*)(lds + PG8_SA(b, h) + aoff + m * 2048 + k * 1024); } while (0)
; #define PG8_LDB(dst, b, h) do { _Pragma("unroll") for (int n = 0; n < 2; ++n) _Pragma("unroll") for (int k = 0; k < 2; ++k) dst[n][k] = *(const LAS bf16x8*)(lds + PG8_SB(b, h) + boff + n * 2048 + k * 1024); } while (0)
; #define PG8_WAIT_V(n) asm volatile("s_waitcnt vmcnt(" #n ")" ::: "memory")
; #define PG8_WAIT_L(n) asm volatile("s_waitcnt lgkmcnt(" #n ")" ::: "memory")
; #define PG8_BAR __builtin_amdgcn_s_barrier()
; #define PG8_SCHED __builtin_amdgcn_sched_barrier(0)
; template <class Epi, class Sched, bool DEFER>
; __device__ __forceinline__ void gemm_fast_core(LAS unsigned char* lds, const GemmP g, const Sched& S, const Epi& E, f32x4 (&acc)[2][2][4][2], Unit& cur) {
;     ...
;         const bool has_next = S.next(ui + 1, nxt);
;         const char* nA = has_next ? (const char*)g.aptr(nxt) : cA; const char* nB = has_next ? (const char*)g.bptr(nxt) : cB;
;         for (int t = 0; t < nt; t += 2) {
;             const bool last = (t == nt - 2);
;             const char* a1 = cA + (size_t)(t + 1) * kstep;
;             const char* a2 = last ? nA : cA + (size_t)(t + 2) * kstep; const char* b2 = last ? nB : cB + (size_t)(t + 2) * kstep;
;             const char* a3 = a2 + kstep; const char* b3 = b2 + kstep;
;             PG8_LDB(B0, 0, 0); PG8_LDB(B1, 0, 1); PG8_SCHED; PG8_LDA(At, 0, 0); PG8_STAGE(PG8_SA(1, 1), a1 + hstepA, voffA);
;             PG8_WAIT_V(8); PG8_WAIT_L(0); PG8_BAR; PG8_MMA(0, 0, At, B0); PG8_MMA(0, 1, At, B1); PG8_BAR; PG8_SCHED;
;             PG8_LDA(At, 0, 1); PG8_STAGE(PG8_SB(0, 0), b2, voffB); PG8_STAGE(PG8_SB(0, 1), b2 + hstepB, voffB); PG8_STAGE(PG8_SA(0, 0), a2, voffA);
;             PG8_WAIT_V(8); PG8_WAIT_L(0); PG8_BAR; PG8_MMA(1, 0, At, B0); PG8_MMA(1, 1, At, B1); PG8_BAR; PG8_SCHED;
.LBB0_235:
	s_ashr_i32 s25, s24, 31
	s_lshl_b64 s[30:31], s[24:25], 20
	s_add_u32 s30, s90, s30
	s_addc_u32 s31, s91, s31
	s_and_b64 s[34:35], s[28:29], exec
	s_cselect_b32 s3, s31, s37
	s_cselect_b32 s25, s30, s36
	s_ashr_i32 s23, s22, 31
	s_lshl_b64 s[34:35], s[22:23], 20
	s_add_u32 s34, s10, s34
	s_addc_u32 s35, s11, s35
	s_and_b64 s[40:41], s[28:29], exec
	s_cselect_b32 s23, s35, s39
	s_cselect_b32 s27, s34, s38
	s_add_u32 s36, s36, 0x80080
	s_addc_u32 s37, s37, 0
	s_add_u32 s33, s38, 0x100
	s_addc_u32 s42, s39, 0
	s_mov_b32 s43, -2
	.p2align 6
	ds_read_b128 v[136:139], v143
	ds_read_b128 v[146:149], v143 offset:1024
	ds_read_b128 v[150:153], v143 offset:2048
	ds_read_b128 v[154:157], v143 offset:3072
	ds_read_b128 v[158:161], v144
	ds_read_b128 v[162:165], v144 offset:1024
	ds_read_b128 v[166:169], v144 offset:2048
	ds_read_b128 v[170:173], v144 offset:3072
	s_add_u32 s38, s36, 0xfff80080
	s_addc_u32 s39, s37, -1
	s_cmp_eq_u32 s43, 28
	s_cselect_b32 s41, s3, s39
	s_cselect_b32 s40, s25, s38
	s_cselect_b32 s39, s23, s42
	s_cselect_b32 s38, s27, s33
	v_lshl_add_u64 v[186:187], s[36:37], 0, v[132:133]
	s_add_i32 m0, s48, 0xc000
	ds_read_b128 v[174:177], v145
	ds_read_b128 v[178:181], v145 offset:1024
	ds_read_b128 v[182:185], v145 offset:2048
	ds_read_b128 v[192:195], v145 offset:3072
	ds_read_b128 v[196:199], v145 offset:4096
	ds_read_b128 v[200:203], v145 offset:5120
	ds_read_b128 v[204:207], v145 offset:6144
	ds_read_b128 v[208:211], v145 offset:7168
	global_load_lds_dwordx4 v[186:187], off
	v_lshl_add_u64 v[186:187], s[36:37], 0, v[134:135]
	s_add_i32 m0, s48, 0xe000
	s_nop 0
	global_load_lds_dwordx4 v[186:187], off
	s_waitcnt vmcnt(8)
	s_waitcnt lgkmcnt(0)
	s_barrier
	s_setprio 1
	s_waitcnt lgkmcnt(0)
	v_mfma_f32_16x16x32_bf16 v[124:127], v[136:139], v[174:177], 0
	v_mfma_f32_16x16x32_bf16 v[120:123], v[150:153], v[174:177], 0
	v_mfma_f32_16x16x32_bf16 v[108:111], v[136:139], v[182:185], 0
	v_mfma_f32_16x16x32_bf16 v[104:107], v[150:153], v[182:185], 0
	v_mfma_f32_16x16x32_bf16 v[92:95], v[136:139], v[196:199], 0
	v_mfma_f32_16x16x32_bf16 v[88:91], v[150:153], v[196:199], 0
	v_mfma_f32_16x16x32_bf16 v[76:79], v[136:139], v[204:207], 0
	v_mfma_f32_16x16x32_bf16 v[72:75], v[150:153], v[204:207], 0
	v_mfma_f32_16x16x32_bf16 v[124:127], v[146:149], v[178:181], v[124:127]
	v_mfma_f32_16x16x32_bf16 v[120:123], v[154:157], v[178:181], v[120:123]
	v_mfma_f32_16x16x32_bf16 v[108:111], v[146:149], v[192:195], v[108:111]
	v_mfma_f32_16x16x32_bf16 v[104:107], v[154:157], v[192:195], v[104:107]
	v_mfma_f32_16x16x32_bf16 v[92:95], v[146:149], v[200:203], v[92:95]
	v_mfma_f32_16x16x32_bf16 v[88:91], v[154:157], v[200:203], v[88:91]
	v_mfma_f32_16x16x32_bf16 v[76:79], v[146:149], v[208:211], v[76:79]
	v_mfma_f32_16x16x32_bf16 v[72:75], v[154:157], v[208:211], v[72:75]
	s_setprio 0
	s_setprio 1
	v_mfma_f32_16x16x32_bf16 v[116:119], v[158:161], v[174:177], 0
	v_mfma_f32_16x16x32_bf16 v[112:115], v[166:169], v[174:177], 0
	v_mfma_f32_16x16x32_bf16 v[100:103], v[158:161], v[182:185], 0
	v_mfma_f32_16x16x32_bf16 v[96:99], v[166:169], v[182:185], 0
	v_mfma_f32_16x16x32_bf16 v[84:87], v[158:161], v[196:199], 0
	v_mfma_f32_16x16x32_bf16 v[80:83], v[166:169], v[196:199], 0
	v_mfma_f32_16x16x32_bf16 v[68:71], v[158:161], v[204:207], 0
	v_mfma_f32_16x16x32_bf16 v[64:67], v[166:169], v[204:207], 0
	v_mfma_f32_16x16x32_bf16 v[116:119], v[162:165], v[178:181], v[116:119]
	v_mfma_f32_16x16x32_bf16 v[112:115], v[170:173], v[178:181], v[112:115]
	v_mfma_f32_16x16x32_bf16 v[100:103], v[162:165], v[192:195], v[100:103]
	v_mfma_f32_16x16x32_bf16 v[96:99], v[170:173], v[192:195], v[96:99]
	v_mfma_f32_16x16x32_bf16 v[84:87], v[162:165], v[200:203], v[84:87]
	v_mfma_f32_16x16x32_bf16 v[80:83], v[170:173], v[200:203], v[80:83]
	v_mfma_f32_16x16x32_bf16 v[68:71], v[162:165], v[208:211], v[68:71]
	v_mfma_f32_16x16x32_bf16 v[64:67], v[170:173], v[208:211], v[64:67]
	s_setprio 0
	s_barrier
	s_add_i32 s44, s76, s21
	v_lshl_add_u64 v[186:187], s[38:39], 0, v[128:129]
	s_mov_b32 m0, s44
	ds_read_b128 v[174:177], v145 offset:16384
	ds_read_b128 v[178:181], v145 offset:17408
	ds_read_b128 v[182:185], v145 offset:18432
	ds_read_b128 v[192:195], v145 offset:19456
	ds_read_b128 v[196:199], v145 offset:20480
	ds_read_b128 v[200:203], v145 offset:21504
	ds_read_b128 v[204:207], v145 offset:22528
	ds_read_b128 v[208:211], v145 offset:23552
	global_load_lds_dwordx4 v[186:187], off
	s_add_i32 m0, s44, 0x2000
	s_add_u32 s44, s38, 0x80000
	v_lshl_add_u64 v[212:213], s[38:39], 0, v[130:131]
	s_addc_u32 s45, s39, 0
	s_add_i32 s46, s77, s21
	global_load_lds_dwordx4 v[212:213], off
	v_lshl_add_u64 v[214:215], s[44:45], 0, v[128:129]
	s_mov_b32 m0, s46
	v_lshl_add_u64 v[216:217], s[40:41], 0, v[130:131]
	global_load_lds_dwordx4 v[214:215], off
	v_lshl_add_u64 v[214:215], s[44:45], 0, v[130:131]
	s_add_i32 m0, s46, 0x2000
	s_nop 0
	global_load_lds_dwordx4 v[214:215], off
	v_lshl_add_u64 v[214:215], s[40:41], 0, v[128:129]
	s_mov_b32 m0, s48
	s_nop 0
	global_load_lds_dwordx4 v[214:215], off
	s_mov_b32 m0, s49
	s_nop 0
	global_load_lds_dwordx4 v[216:217], off
	s_waitcnt vmcnt(8)
	s_waitcnt lgkmcnt(0)
	s_barrier
; #define PG8_STAGE(bufoff, gbase, voff) do { _Pragma("unroll") for (int _i = 0; _i < 2; ++_i) \
;         __builtin_amdgcn_global_load_lds((const unsigned*)((const char*)(gbase) + (voff)[_i]), (LAS unsigned*)(lds + (bufoff) + ldsw + _i * 8192), 16, 0, 0); } while (0)
; #define PG8_LDA(dst, b, h) do { _Pragma("unroll") for (int m = 0; m < 4; ++m) _Pragma("unroll") for (int k = 0; k < 2; ++k) dst[m][k] = *(const LAS bf16x8*)(lds + PG8_SA(b, h) + aoff + m * 2048 + k * 1024); } while (0)
; #define PG8_LDB(dst, b, h) do { _Pragma("unroll") for (int n = 0; n < 2; ++n) _Pragma("unroll") for (int k = 0; k < 2; ++k) dst[n][k] = *(const LAS bf16x8*)(lds + PG8_SB(b, h) + boff + n * 2048 + k * 1024); } while (0)
; #define PG8_MMA(ai, bj, At, Bt) do { __builtin_amdgcn_s_setprio(1); _Pragma("unroll") for (int m = 0; m < 4; ++m) _Pragma("unroll") for (int n = 0; n < 2; ++n) _Pragma("unroll") for (int k = 0; k < 2; ++k) \
;         acc[ai][bj][m][n] = __builtin_amdgcn_mfma_f32_16x16x32_bf16(Bt[n][k], At[m][k], acc[ai][bj][m][n], 0, 0, 0); __builtin_amdgcn_s_setprio(0); } while (0)
; #define PG8_WAIT_V(n) asm volatile("s_waitcnt vmcnt(" #n ")" ::: "memory")
; #define PG8_WAIT_L(n) asm volatile("s_waitcnt lgkmcnt(" #n ")" ::: "memory")
; #define PG8_BAR __builtin_amdgcn_s_barrier()
; #define PG8_SCHED __builtin_amdgcn_sched_barrier(0)
; template <class Epi, class Sched, bool DEFER>
; __device__ __forceinline__ void gemm_fast_core(LAS unsigned char* lds, const GemmP g, const Sched& S, const Epi& E, f32x4 (&acc)[2][2][4][2], Unit& cur) {
;     ...
;             PG8_WAIT_V(8); PG8_WAIT_L(0); PG8_BAR; PG8_MMA(1, 0, At, B0); PG8_MMA(1, 1, At, B1); PG8_BAR; PG8_SCHED;
;             PG8_LDB(B0, 1, 0); PG8_LDB(B1, 1, 1); PG8_SCHED; PG8_LDA(At, 1, 0); PG8_STAGE(PG8_SA(0, 1), a2 + hstepA, voffA);
;             PG8_WAIT_V(8); PG8_WAIT_L(0); PG8_BAR; PG8_MMA(0, 0, At, B0); PG8_MMA(0, 1, At, B1); PG8_BAR; PG8_SCHED;
;             PG8_LDA(At, 1, 1); PG8_STAGE(PG8_SB(1, 0), b3, voffB); PG8_STAGE(PG8_SB(1, 1), b3 + hstepB, voffB); PG8_STAGE(PG8_SA(1, 0), a3, voffA);
;             PG8_WAIT_V(8); PG8_WAIT_L(0); PG8_BAR; PG8_MMA(1, 0, At, B0); PG8_MMA(1, 1, At, B1); PG8_BAR; PG8_SCHED;
	s_setprio 1
	s_waitcnt lgkmcnt(0)
	v_mfma_f32_16x16x32_bf16 v[60:63], v[136:139], v[174:177], 0
	v_mfma_f32_16x16x32_bf16 v[56:59], v[150:153], v[174:177], 0
	v_mfma_f32_16x16x32_bf16 v[44:47], v[136:139], v[182:185], 0
	v_mfma_f32_16x16x32_bf16 v[40:43], v[150:153], v[182:185], 0
	v_mfma_f32_16x16x32_bf16 v[28:31], v[136:139], v[196:199], 0
	v_mfma_f32_16x16x32_bf16 v[24:27], v[150:153], v[196:199], 0
	v_mfma_f32_16x16x32_bf16 v[12:15], v[136:139], v[204:207], 0
	v_mfma_f32_16x16x32_bf16 v[8:11], v[150:153], v[204:207], 0
	v_mfma_f32_16x16x32_bf16 v[60:63], v[146:149], v[178:181], v[60:63]
	v_mfma_f32_16x16x32_bf16 v[56:59], v[154:157], v[178:181], v[56:59]
	v_mfma_f32_16x16x32_bf16 v[44:47], v[146:149], v[192:195], v[44:47]
	v_mfma_f32_16x16x32_bf16 v[40:43], v[154:157], v[192:195], v[40:43]
	v_mfma_f32_16x16x32_bf16 v[28:31], v[146:149], v[200:203], v[28:31]
	v_mfma_f32_16x16x32_bf16 v[24:27], v[154:157], v[200:203], v[24:27]
	v_mfma_f32_16x16x32_bf16 v[12:15], v[146:149], v[208:211], v[12:15]
	v_mfma_f32_16x16x32_bf16 v[8:11], v[154:157], v[208:211], v[8:11]
	s_setprio 0
	s_setprio 1
	v_mfma_f32_16x16x32_bf16 v[52:55], v[158:161], v[174:177], 0
	v_mfma_f32_16x16x32_bf16 v[48:51], v[166:169], v[174:177], 0
	v_mfma_f32_16x16x32_bf16 v[36:39], v[158:161], v[182:185], 0
	v_mfma_f32_16x16x32_bf16 v[32:35], v[166:169], v[182:185], 0
	v_mfma_f32_16x16x32_bf16 v[20:23], v[158:161], v[196:199], 0
	v_mfma_f32_16x16x32_bf16 v[16:19], v[166:169], v[196:199], 0
	v_mfma_f32_16x16x32_bf16 v[4:7], v[158:161], v[204:207], 0
	v_mfma_f32_16x16x32_bf16 v[0:3], v[166:169], v[204:207], 0
	v_mfma_f32_16x16x32_bf16 v[52:55], v[162:165], v[178:181], v[52:55]
	v_mfma_f32_16x16x32_bf16 v[48:51], v[170:173], v[178:181], v[48:51]
	v_mfma_f32_16x16x32_bf16 v[36:39], v[162:165], v[192:195], v[36:39]
	v_mfma_f32_16x16x32_bf16 v[32:35], v[170:173], v[192:195], v[32:35]
	v_mfma_f32_16x16x32_bf16 v[20:23], v[162:165], v[200:203], v[20:23]
	v_mfma_f32_16x16x32_bf16 v[16:19], v[170:173], v[200:203], v[16:19]
	v_mfma_f32_16x16x32_bf16 v[4:7], v[162:165], v[208:211], v[4:7]
	v_mfma_f32_16x16x32_bf16 v[0:3], v[170:173], v[208:211], v[0:3]
	s_setprio 0
	s_barrier
	s_add_i32 s44, 0, 0x18000
	s_add_i32 s45, 0, 0x1c000
	v_add_u32_e32 v154, s44, v141
	v_add_u32_e32 v170, s45, v141
	ds_read_b128 v[136:139], v154
	ds_read_b128 v[146:149], v154 offset:1024
	ds_read_b128 v[150:153], v154 offset:2048
	ds_read_b128 v[154:157], v154 offset:3072
	ds_read_b128 v[158:161], v170
	ds_read_b128 v[162:165], v170 offset:1024
	ds_read_b128 v[166:169], v170 offset:2048
	ds_read_b128 v[170:173], v170 offset:3072
	s_add_u32 s40, s40, 0x80000
	s_addc_u32 s41, s41, 0
	s_mov_b32 m0, s68
	v_lshl_add_u64 v[218:219], s[40:41], 0, v[128:129]
	ds_read_b128 v[174:177], v145 offset:32768
	ds_read_b128 v[178:181], v145 offset:33792
	ds_read_b128 v[182:185], v145 offset:34816
	ds_read_b128 v[192:195], v145 offset:35840
	ds_read_b128 v[196:199], v145 offset:36864
	ds_read_b128 v[200:203], v145 offset:37888
	ds_read_b128 v[204:207], v145 offset:38912
	ds_read_b128 v[208:211], v145 offset:39936
	global_load_lds_dwordx4 v[218:219], off
	v_lshl_add_u64 v[218:219], s[40:41], 0, v[130:131]
	s_mov_b32 m0, s69
	s_nop 0
	global_load_lds_dwordx4 v[218:219], off
	s_waitcnt vmcnt(8)
	s_waitcnt lgkmcnt(0)
	s_barrier
	s_setprio 1
	s_waitcnt lgkmcnt(0)
	v_mfma_f32_16x16x32_bf16 v[124:127], v[136:139], v[174:177], v[124:127]
	v_mfma_f32_16x16x32_bf16 v[120:123], v[150:153], v[174:177], v[120:123]
	v_mfma_f32_16x16x32_bf16 v[108:111], v[136:139], v[182:185], v[108:111]
	v_mfma_f32_16x16x32_bf16 v[104:107], v[150:153], v[182:185], v[104:107]
	v_mfma_f32_16x16x32_bf16 v[92:95], v[136:139], v[196:199], v[92:95]
	v_mfma_f32_16x16x32_bf16 v[88:91], v[150:153], v[196:199], v[88:91]
	v_mfma_f32_16x16x32_bf16 v[76:79], v[136:139], v[204:207], v[76:79]
	v_mfma_f32_16x16x32_bf16 v[72:75], v[150:153], v[204:207], v[72:75]
	v_mfma_f32_16x16x32_bf16 v[124:127], v[146:149], v[178:181], v[124:127]
	v_mfma_f32_16x16x32_bf16 v[120:123], v[154:157], v[178:181], v[120:123]
	v_mfma_f32_16x16x32_bf16 v[108:111], v[146:149], v[192:195], v[108:111]
	v_mfma_f32_16x16x32_bf16 v[104:107], v[154:157], v[192:195], v[104:107]
	v_mfma_f32_16x16x32_bf16 v[92:95], v[146:149], v[200:203], v[92:95]
	v_mfma_f32_16x16x32_bf16 v[88:91], v[154:157], v[200:203], v[88:91]
	v_mfma_f32_16x16x32_bf16 v[76:79], v[146:149], v[208:211], v[76:79]
	v_mfma_f32_16x16x32_bf16 v[72:75], v[154:157], v[208:211], v[72:75]
	s_setprio 0
	s_setprio 1
	v_mfma_f32_16x16x32_bf16 v[116:119], v[158:161], v[174:177], v[116:119]
	v_mfma_f32_16x16x32_bf16 v[112:115], v[166:169], v[174:177], v[112:115]
	v_mfma_f32_16x16x32_bf16 v[100:103], v[158:161], v[182:185], v[100:103]
	v_mfma_f32_16x16x32_bf16 v[96:99], v[166:169], v[182:185], v[96:99]
	v_mfma_f32_16x16x32_bf16 v[84:87], v[158:161], v[196:199], v[84:87]
	v_mfma_f32_16x16x32_bf16 v[80:83], v[166:169], v[196:199], v[80:83]
	v_mfma_f32_16x16x32_bf16 v[68:71], v[158:161], v[204:207], v[68:71]
	v_mfma_f32_16x16x32_bf16 v[64:67], v[166:169], v[204:207], v[64:67]
	v_mfma_f32_16x16x32_bf16 v[116:119], v[162:165], v[178:181], v[116:119]
	v_mfma_f32_16x16x32_bf16 v[112:115], v[170:173], v[178:181], v[112:115]
	v_mfma_f32_16x16x32_bf16 v[100:103], v[162:165], v[192:195], v[100:103]
	v_mfma_f32_16x16x32_bf16 v[96:99], v[170:173], v[192:195], v[96:99]
	v_mfma_f32_16x16x32_bf16 v[84:87], v[162:165], v[200:203], v[84:87]
	v_mfma_f32_16x16x32_bf16 v[80:83], v[170:173], v[200:203], v[80:83]
	v_mfma_f32_16x16x32_bf16 v[68:71], v[162:165], v[208:211], v[68:71]
	v_mfma_f32_16x16x32_bf16 v[64:67], v[170:173], v[208:211], v[64:67]
	s_setprio 0
	s_barrier
; #define PG8_STAGE(bufoff, gbase, voff) do { _Pragma("unroll") for (int _i = 0; _i < 2; ++_i) \
;         __builtin_amdgcn_global_load_lds((const unsigned*)((const char*)(gbase) + (voff)[_i]), (LAS unsigned*)(lds + (bufoff) + ldsw + _i * 8192), 16, 0, 0); } while (0)
; #define PG8_LDA(dst, b, h) do { _Pragma("unroll") for (int m = 0; m < 4; ++m) _Pragma("unroll") for (int k = 0; k < 2; ++k) dst[m][k] = *(const LAS bf16x8*)(lds + PG8_SA(b, h) + aoff + m * 2048 + k * 1024); } while (0)
; #define PG8_MMA(ai, bj, At, Bt) do { __builtin_amdgcn_s_setprio(1); _Pragma("unroll") for (int m = 0; m < 4; ++m) _Pragma("unroll") for (int n = 0; n < 2; ++n) _Pragma("unroll") for (int k = 0; k < 2; ++k) \
;         acc[ai][bj][m][n] = __builtin_amdgcn_mfma_f32_16x16x32_bf16(Bt[n][k], At[m][k], acc[ai][bj][m][n], 0, 0, 0); __builtin_amdgcn_s_setprio(0); } while (0)
; #define PG8_WAIT_V(n) asm volatile("s_waitcnt vmcnt(" #n ")" ::: "memory")
; #define PG8_WAIT_L(n) asm volatile("s_waitcnt lgkmcnt(" #n ")" ::: "memory")
; #define PG8_BAR __builtin_amdgcn_s_barrier()
; #define PG8_SCHED __builtin_amdgcn_sched_barrier(0)
; template <class Epi, class Sched, bool DEFER>
; __device__ __forceinline__ void gemm_fast_core(LAS unsigned char* lds, const GemmP g, const Sched& S, const Epi& E, f32x4 (&acc)[2][2][4][2], Unit& cur) {
;     ...
;         for (int t = 0; t < nt; t += 2) {
;     ...
;             PG8_LDA(At, 1, 1); PG8_STAGE(PG8_SB(1, 0), b3, voffB); PG8_STAGE(PG8_SB(1, 1), b3 + hstepB, voffB); PG8_STAGE(PG8_SA(1, 0), a3, voffA);
;             PG8_WAIT_V(8); PG8_WAIT_L(0); PG8_BAR; PG8_MMA(1, 0, At, B0); PG8_MMA(1, 1, At, B1); PG8_BAR; PG8_SCHED;
	s_add_i32 s40, s44, s21
	v_lshl_add_u64 v[186:187], v[186:187], 0, s[16:17]
	s_mov_b32 m0, s40
	ds_read_b128 v[174:177], v145 offset:49152
	ds_read_b128 v[178:181], v145 offset:50176
	ds_read_b128 v[182:185], v145 offset:51200
	ds_read_b128 v[192:195], v145 offset:52224
	ds_read_b128 v[196:199], v145 offset:53248
	ds_read_b128 v[200:203], v145 offset:54272
	ds_read_b128 v[204:207], v145 offset:55296
	ds_read_b128 v[208:211], v145 offset:56320
	global_load_lds_dwordx4 v[186:187], off
	s_add_i32 m0, s40, 0x2000
	s_add_u32 s38, s38, 0x80080
	v_lshl_add_u64 v[186:187], v[212:213], 0, s[16:17]
	s_addc_u32 s39, s39, 0
	s_add_i32 s40, s45, s21
	global_load_lds_dwordx4 v[186:187], off
	v_lshl_add_u64 v[186:187], s[38:39], 0, v[128:129]
	s_mov_b32 m0, s40
	s_nop 0
	global_load_lds_dwordx4 v[186:187], off
	v_lshl_add_u64 v[186:187], s[38:39], 0, v[130:131]
	s_add_i32 m0, s40, 0x2000
	s_nop 0
	global_load_lds_dwordx4 v[186:187], off
	v_lshl_add_u64 v[186:187], v[214:215], 0, s[16:17]
	s_mov_b32 m0, s74
	s_nop 0
	global_load_lds_dwordx4 v[186:187], off
	v_lshl_add_u64 v[186:187], v[216:217], 0, s[16:17]
	s_mov_b32 m0, s75
	s_nop 0
	global_load_lds_dwordx4 v[186:187], off
	s_waitcnt vmcnt(8)
	s_waitcnt lgkmcnt(0)
	s_barrier
	s_setprio 1
	s_waitcnt lgkmcnt(0)
	v_mfma_f32_16x16x32_bf16 v[60:63], v[136:139], v[174:177], v[60:63]
	v_mfma_f32_16x16x32_bf16 v[56:59], v[150:153], v[174:177], v[56:59]
	v_mfma_f32_16x16x32_bf16 v[44:47], v[136:139], v[182:185], v[44:47]
	v_mfma_f32_16x16x32_bf16 v[40:43], v[150:153], v[182:185], v[40:43]
	v_mfma_f32_16x16x32_bf16 v[28:31], v[136:139], v[196:199], v[28:31]
	v_mfma_f32_16x16x32_bf16 v[24:27], v[150:153], v[196:199], v[24:27]
	v_mfma_f32_16x16x32_bf16 v[12:15], v[136:139], v[204:207], v[12:15]
	v_mfma_f32_16x16x32_bf16 v[8:11], v[150:153], v[204:207], v[8:11]
	v_mfma_f32_16x16x32_bf16 v[60:63], v[146:149], v[178:181], v[60:63]
	v_mfma_f32_16x16x32_bf16 v[56:59], v[154:157], v[178:181], v[56:59]
	v_mfma_f32_16x16x32_bf16 v[44:47], v[146:149], v[192:195], v[44:47]
	v_mfma_f32_16x16x32_bf16 v[40:43], v[154:157], v[192:195], v[40:43]
	v_mfma_f32_16x16x32_bf16 v[28:31], v[146:149], v[200:203], v[28:31]
	v_mfma_f32_16x16x32_bf16 v[24:27], v[154:157], v[200:203], v[24:27]
	v_mfma_f32_16x16x32_bf16 v[12:15], v[146:149], v[208:211], v[12:15]
	v_mfma_f32_16x16x32_bf16 v[8:11], v[154:157], v[208:211], v[8:11]
	s_setprio 0
	s_setprio 1
	v_mfma_f32_16x16x32_bf16 v[52:55], v[158:161], v[174:177], v[52:55]
	v_mfma_f32_16x16x32_bf16 v[48:51], v[166:169], v[174:177], v[48:51]
	v_mfma_f32_16x16x32_bf16 v[36:39], v[158:161], v[182:185], v[36:39]
	v_mfma_f32_16x16x32_bf16 v[32:35], v[166:169], v[182:185], v[32:35]
	v_mfma_f32_16x16x32_bf16 v[20:23], v[158:161], v[196:199], v[20:23]
	v_mfma_f32_16x16x32_bf16 v[16:19], v[166:169], v[196:199], v[16:19]
	v_mfma_f32_16x16x32_bf16 v[4:7], v[158:161], v[204:207], v[4:7]
	v_mfma_f32_16x16x32_bf16 v[0:3], v[166:169], v[204:207], v[0:3]
	v_mfma_f32_16x16x32_bf16 v[52:55], v[162:165], v[178:181], v[52:55]
	v_mfma_f32_16x16x32_bf16 v[48:51], v[170:173], v[178:181], v[48:51]
	v_mfma_f32_16x16x32_bf16 v[36:39], v[162:165], v[192:195], v[36:39]
	v_mfma_f32_16x16x32_bf16 v[32:35], v[170:173], v[192:195], v[32:35]
	v_mfma_f32_16x16x32_bf16 v[20:23], v[162:165], v[200:203], v[20:23]
	v_mfma_f32_16x16x32_bf16 v[16:19], v[170:173], v[200:203], v[16:19]
	v_mfma_f32_16x16x32_bf16 v[4:7], v[162:165], v[208:211], v[4:7]
	v_mfma_f32_16x16x32_bf16 v[0:3], v[170:173], v[208:211], v[0:3]
	s_setprio 0
	s_barrier
	s_add_i32 s43, s43, 2
	s_add_u32 s36, s36, 0x100
	s_addc_u32 s37, s37, 0
	s_add_u32 s33, s33, 0x100
	s_addc_u32 s42, s42, 0
	s_cmp_gt_u32 s43, 29
	s_cbranch_scc0 .LBB0_236
	s_branch .Lpeel_p2_done
	.p2align 6

; #define PG8_BAR __builtin_amdgcn_s_barrier()
; template <class Epi, class Sched, bool DEFER>
; __device__ __forceinline__ void gemm_fast_core(LAS unsigned char* lds, const GemmP g, const Sched& S, const Epi& E, f32x4 (&acc)[2][2][4][2], Unit& cur) {
;     ...
;         if (wr == 0) PG8_BAR;
.Lpeel_p2_done:
	s_and_b64 vcc, exec, s[18:19]
	s_cbranch_vccz .LBB0_239
	s_barrier

;     __device__ __forceinline__ bool next(int i, Unit& u) const { return decode(i * G + c, u); }
; #define PG8_STAGE(bufoff, gbase, voff) do { _Pragma("unroll") for (int _i = 0; _i < 2; ++_i) \
;         __builtin_amdgcn_global_load_lds((const unsigned*)((const char*)(gbase) + (voff)[_i]), (LAS unsigned*)(lds + (bufoff) + ldsw + _i * 8192), 16, 0, 0); } while (0)
; #define PG8_LDA(dst, b, h) do { _Pragma("unroll") for (int m = 0; m < 4; ++m) _Pragma("unroll") for (int k = 0; k < 2; ++k) dst[m][k] = *(const LAS bf16x8*)(lds + PG8_SA(b, h) + aoff + m * 2048 + k * 1024); } while (0)
; #define PG8_LDB(dst, b, h) do { _Pragma("unroll") for (int n = 0; n < 2; ++n) _Pragma("unroll") for (int k = 0; k < 2; ++k) dst[n][k] = *(const LAS bf16x8*)(lds + PG8_SB(b, h) + boff + n * 2048 + k * 1024); } while (0)
; #define PG8_WAIT_V(n) asm volatile("s_waitcnt vmcnt(" #n ")" ::: "memory")
; #define PG8_WAIT_L(n) asm volatile("s_waitcnt lgkmcnt(" #n ")" ::: "memory")
; #define PG8_BAR __builtin_amdgcn_s_barrier()
; #define PG8_SCHED __builtin_amdgcn_sched_barrier(0)
; template <class Epi, class Sched, bool DEFER>
; __device__ __forceinline__ void gemm_fast_core(LAS unsigned char* lds, const GemmP g, const Sched& S, const Epi& E, f32x4 (&acc)[2][2][4][2], Unit& cur) {
;     ...
;         const bool has_next = S.next(ui + 1, nxt);
;         const char* nA = has_next ? (const char*)g.aptr(nxt) : cA; const char* nB = has_next ? (const char*)g.bptr(nxt) : cB;
;         for (int t = 0; t < nt; t += 2) {
;             const bool last = (t == nt - 2);
;             const char* a1 = cA + (size_t)(t + 1) * kstep;
;             const char* a2 = last ? nA : cA + (size_t)(t + 2) * kstep; const char* b2 = last ? nB : cB + (size_t)(t + 2) * kstep;
;             const char* a3 = a2 + kstep; const char* b3 = b2 + kstep;
;             PG8_LDB(B0, 0, 0); PG8_LDB(B1, 0, 1); PG8_SCHED; PG8_LDA(At, 0, 0); PG8_STAGE(PG8_SA(1, 1), a1 + hstepA, voffA);
;             PG8_WAIT_V(8); PG8_WAIT_L(0); PG8_BAR; PG8_MMA(0, 0, At, B0); PG8_MMA(0, 1, At, B1); PG8_BAR; PG8_SCHED;
;             PG8_LDA(At, 0, 1); PG8_STAGE(PG8_SB(0, 0), b2, voffB); PG8_STAGE(PG8_SB(0, 1), b2 + hstepB, voffB); PG8_STAGE(PG8_SA(0, 0), a2, voffA);
;             PG8_WAIT_V(8); PG8_WAIT_L(0); PG8_BAR; PG8_MMA(1, 0, At, B0); PG8_MMA(1, 1, At, B1); PG8_BAR; PG8_SCHED;
.LBB0_1798:
	s_ashr_i32 s19, s18, 31
	s_lshl_b64 s[22:23], s[18:19], 20
	s_add_u32 s22, s90, s22
	s_addc_u32 s23, s91, s23
	s_and_b64 s[24:25], s[20:21], exec
	s_cselect_b32 s19, s23, s29
	s_cselect_b32 s47, s22, s28
	s_ashr_i32 s17, s16, 31
	s_lshl_b64 s[24:25], s[16:17], 20
	s_add_u32 s24, s96, s24
	s_addc_u32 s25, s97, s25
	s_and_b64 s[34:35], s[20:21], exec
	s_cselect_b32 s17, s25, s31
	s_cselect_b32 s48, s24, s30
	s_add_u32 s28, s28, 0x80080
	s_addc_u32 s29, s29, 0
	s_add_u32 s49, s30, 0x100
	s_addc_u32 s50, s31, 0
	s_mov_b32 s51, -2
	.p2align 6
	ds_read_b128 v[120:123], v205
	ds_read_b128 v[124:127], v205 offset:1024
	ds_read_b128 v[128:131], v205 offset:2048
	ds_read_b128 v[132:135], v205 offset:3072
	ds_read_b128 v[136:139], v206
	ds_read_b128 v[140:143], v206 offset:1024
	ds_read_b128 v[144:147], v206 offset:2048
	ds_read_b128 v[148:151], v206 offset:3072
	s_add_u32 s30, s28, 0xfff80080
	s_addc_u32 s31, s29, -1
	s_cmp_eq_u32 s51, 28
	s_cselect_b32 s35, s19, s31
	s_cselect_b32 s34, s47, s30
	s_cselect_b32 s31, s17, s50
	s_cselect_b32 s30, s48, s49
	v_lshl_add_u64 v[220:221], s[28:29], 0, v[164:165]
	s_add_i32 m0, s27, 0xc000
	ds_read_b128 v[168:171], v207
	ds_read_b128 v[172:175], v207 offset:1024
	ds_read_b128 v[176:179], v207 offset:2048
	ds_read_b128 v[180:183], v207 offset:3072
	ds_read_b128 v[184:187], v207 offset:4096
	ds_read_b128 v[208:211], v207 offset:5120
	ds_read_b128 v[212:215], v207 offset:6144
	ds_read_b128 v[216:219], v207 offset:7168
	global_load_lds_dwordx4 v[220:221], off
	v_lshl_add_u64 v[220:221], s[28:29], 0, v[166:167]
	s_add_i32 m0, s27, 0xe000
	s_nop 0
	global_load_lds_dwordx4 v[220:221], off
	s_waitcnt vmcnt(8)
	s_waitcnt lgkmcnt(0)
	s_barrier
	s_setprio 1
	s_waitcnt lgkmcnt(0)
	v_mfma_f32_16x16x32_bf16 v[156:159], v[120:123], v[168:171], 0
	v_mfma_f32_16x16x32_bf16 v[60:63], v[128:131], v[168:171], 0
	v_mfma_f32_16x16x32_bf16 v[116:119], v[120:123], v[176:179], 0
	v_mfma_f32_16x16x32_bf16 v[52:55], v[128:131], v[176:179], 0
	v_mfma_f32_16x16x32_bf16 v[108:111], v[120:123], v[184:187], 0
	v_mfma_f32_16x16x32_bf16 v[44:47], v[128:131], v[184:187], 0
	v_mfma_f32_16x16x32_bf16 v[100:103], v[120:123], v[212:215], 0
	v_mfma_f32_16x16x32_bf16 v[36:39], v[128:131], v[212:215], 0
	v_mfma_f32_16x16x32_bf16 v[156:159], v[124:127], v[172:175], v[156:159]
	v_mfma_f32_16x16x32_bf16 v[60:63], v[132:135], v[172:175], v[60:63]
	v_mfma_f32_16x16x32_bf16 v[116:119], v[124:127], v[180:183], v[116:119]
	v_mfma_f32_16x16x32_bf16 v[52:55], v[132:135], v[180:183], v[52:55]
	v_mfma_f32_16x16x32_bf16 v[108:111], v[124:127], v[208:211], v[108:111]
	v_mfma_f32_16x16x32_bf16 v[44:47], v[132:135], v[208:211], v[44:47]
	v_mfma_f32_16x16x32_bf16 v[100:103], v[124:127], v[216:219], v[100:103]
	v_mfma_f32_16x16x32_bf16 v[36:39], v[132:135], v[216:219], v[36:39]
	s_setprio 0
	s_setprio 1
	v_mfma_f32_16x16x32_bf16 v[152:155], v[136:139], v[168:171], 0
	v_mfma_f32_16x16x32_bf16 v[56:59], v[144:147], v[168:171], 0
	v_mfma_f32_16x16x32_bf16 v[112:115], v[136:139], v[176:179], 0
	v_mfma_f32_16x16x32_bf16 v[48:51], v[144:147], v[176:179], 0
	v_mfma_f32_16x16x32_bf16 v[104:107], v[136:139], v[184:187], 0
	v_mfma_f32_16x16x32_bf16 v[40:43], v[144:147], v[184:187], 0
	v_mfma_f32_16x16x32_bf16 v[96:99], v[136:139], v[212:215], 0
	v_mfma_f32_16x16x32_bf16 v[32:35], v[144:147], v[212:215], 0
	v_mfma_f32_16x16x32_bf16 v[152:155], v[140:143], v[172:175], v[152:155]
	v_mfma_f32_16x16x32_bf16 v[56:59], v[148:151], v[172:175], v[56:59]
	v_mfma_f32_16x16x32_bf16 v[112:115], v[140:143], v[180:183], v[112:115]
	v_mfma_f32_16x16x32_bf16 v[48:51], v[148:151], v[180:183], v[48:51]
	v_mfma_f32_16x16x32_bf16 v[104:107], v[140:143], v[208:211], v[104:107]
	v_mfma_f32_16x16x32_bf16 v[40:43], v[148:151], v[208:211], v[40:43]
	v_mfma_f32_16x16x32_bf16 v[96:99], v[140:143], v[216:219], v[96:99]
	v_mfma_f32_16x16x32_bf16 v[32:35], v[148:151], v[216:219], v[32:35]
	s_setprio 0
	s_barrier
	s_add_i32 s52, s44, s36
	v_lshl_add_u64 v[220:221], s[30:31], 0, v[162:163]
	s_mov_b32 m0, s52
	ds_read_b128 v[168:171], v207 offset:16384
	ds_read_b128 v[172:175], v207 offset:17408
	ds_read_b128 v[176:179], v207 offset:18432
	ds_read_b128 v[180:183], v207 offset:19456
	ds_read_b128 v[184:187], v207 offset:20480
	ds_read_b128 v[208:211], v207 offset:21504
	ds_read_b128 v[212:215], v207 offset:22528
	ds_read_b128 v[216:219], v207 offset:23552
	global_load_lds_dwordx4 v[220:221], off
	s_add_i32 m0, s52, 0x2000
	s_add_u32 s52, s30, 0x80000
	v_lshl_add_u64 v[222:223], s[30:31], 0, v[160:161]
	s_addc_u32 s53, s31, 0
	s_add_i32 s54, s45, s36
	global_load_lds_dwordx4 v[222:223], off
	v_lshl_add_u64 v[224:225], s[52:53], 0, v[162:163]
	s_mov_b32 m0, s54
	v_lshl_add_u64 v[226:227], s[34:35], 0, v[192:193]
	global_load_lds_dwordx4 v[224:225], off
	v_lshl_add_u64 v[224:225], s[52:53], 0, v[160:161]
	s_add_i32 m0, s54, 0x2000
	s_nop 0
	global_load_lds_dwordx4 v[224:225], off
	v_lshl_add_u64 v[224:225], s[34:35], 0, v[190:191]
	s_mov_b32 m0, s27
	s_nop 0
	global_load_lds_dwordx4 v[224:225], off
	s_mov_b32 m0, s38
	s_nop 0
	global_load_lds_dwordx4 v[226:227], off
	s_waitcnt vmcnt(8)
	s_waitcnt lgkmcnt(0)
	s_barrier
; #define PG8_STAGE(bufoff, gbase, voff) do { _Pragma("unroll") for (int _i = 0; _i < 2; ++_i) \
;         __builtin_amdgcn_global_load_lds((const unsigned*)((const char*)(gbase) + (voff)[_i]), (LAS unsigned*)(lds + (bufoff) + ldsw + _i * 8192), 16, 0, 0); } while (0)
; #define PG8_LDA(dst, b, h) do { _Pragma("unroll") for (int m = 0; m < 4; ++m) _Pragma("unroll") for (int k = 0; k < 2; ++k) dst[m][k] = *(const LAS bf16x8*)(lds + PG8_SA(b, h) + aoff + m * 2048 + k * 1024); } while (0)
; #define PG8_LDB(dst, b, h) do { _Pragma("unroll") for (int n = 0; n < 2; ++n) _Pragma("unroll") for (int k = 0; k < 2; ++k) dst[n][k] = *(const LAS bf16x8*)(lds + PG8_SB(b, h) + boff + n * 2048 + k * 1024); } while (0)
; #define PG8_MMA(ai, bj, At, Bt) do { __builtin_amdgcn_s_setprio(1); _Pragma("unroll") for (int m = 0; m < 4; ++m) _Pragma("unroll") for (int n = 0; n < 2; ++n) _Pragma("unroll") for (int k = 0; k < 2; ++k) \
;         acc[ai][bj][m][n] = __builtin_amdgcn_mfma_f32_16x16x32_bf16(Bt[n][k], At[m][k], acc[ai][bj][m][n], 0, 0, 0); __builtin_amdgcn_s_setprio(0); } while (0)
; #define PG8_WAIT_V(n) asm volatile("s_waitcnt vmcnt(" #n ")" ::: "memory")
; #define PG8_WAIT_L(n) asm volatile("s_waitcnt lgkmcnt(" #n ")" ::: "memory")
; #define PG8_BAR __builtin_amdgcn_s_barrier()
; #define PG8_SCHED __builtin_amdgcn_sched_barrier(0)
; template <class Epi, class Sched, bool DEFER>
; __device__ __forceinline__ void gemm_fast_core(LAS unsigned char* lds, const GemmP g, const Sched& S, const Epi& E, f32x4 (&acc)[2][2][4][2], Unit& cur) {
;     ...
;             PG8_WAIT_V(8); PG8_WAIT_L(0); PG8_BAR; PG8_MMA(1, 0, At, B0); PG8_MMA(1, 1, At, B1); PG8_BAR; PG8_SCHED;
;             PG8_LDB(B0, 1, 0); PG8_LDB(B1, 1, 1); PG8_SCHED; PG8_LDA(At, 1, 0); PG8_STAGE(PG8_SA(0, 1), a2 + hstepA, voffA);
;             PG8_WAIT_V(8); PG8_WAIT_L(0); PG8_BAR; PG8_MMA(0, 0, At, B0); PG8_MMA(0, 1, At, B1); PG8_BAR; PG8_SCHED;
;             PG8_LDA(At, 1, 1); PG8_STAGE(PG8_SB(1, 0), b3, voffB); PG8_STAGE(PG8_SB(1, 1), b3 + hstepB, voffB); PG8_STAGE(PG8_SA(1, 0), a3, voffA);
;             PG8_WAIT_V(8); PG8_WAIT_L(0); PG8_BAR; PG8_MMA(1, 0, At, B0); PG8_MMA(1, 1, At, B1); PG8_BAR; PG8_SCHED;
	s_setprio 1
	s_waitcnt lgkmcnt(0)
	v_mfma_f32_16x16x32_bf16 v[92:95], v[120:123], v[168:171], 0
	v_mfma_f32_16x16x32_bf16 v[28:31], v[128:131], v[168:171], 0
	v_mfma_f32_16x16x32_bf16 v[84:87], v[120:123], v[176:179], 0
	v_mfma_f32_16x16x32_bf16 v[20:23], v[128:131], v[176:179], 0
	v_mfma_f32_16x16x32_bf16 v[76:79], v[120:123], v[184:187], 0
	v_mfma_f32_16x16x32_bf16 v[12:15], v[128:131], v[184:187], 0
	v_mfma_f32_16x16x32_bf16 v[68:71], v[120:123], v[212:215], 0
	v_mfma_f32_16x16x32_bf16 v[4:7], v[128:131], v[212:215], 0
	v_mfma_f32_16x16x32_bf16 v[92:95], v[124:127], v[172:175], v[92:95]
	v_mfma_f32_16x16x32_bf16 v[28:31], v[132:135], v[172:175], v[28:31]
	v_mfma_f32_16x16x32_bf16 v[84:87], v[124:127], v[180:183], v[84:87]
	v_mfma_f32_16x16x32_bf16 v[20:23], v[132:135], v[180:183], v[20:23]
	v_mfma_f32_16x16x32_bf16 v[76:79], v[124:127], v[208:211], v[76:79]
	v_mfma_f32_16x16x32_bf16 v[12:15], v[132:135], v[208:211], v[12:15]
	v_mfma_f32_16x16x32_bf16 v[68:71], v[124:127], v[216:219], v[68:71]
	v_mfma_f32_16x16x32_bf16 v[4:7], v[132:135], v[216:219], v[4:7]
	s_setprio 0
	s_setprio 1
	v_mfma_f32_16x16x32_bf16 v[88:91], v[136:139], v[168:171], 0
	v_mfma_f32_16x16x32_bf16 v[24:27], v[144:147], v[168:171], 0
	v_mfma_f32_16x16x32_bf16 v[80:83], v[136:139], v[176:179], 0
	v_mfma_f32_16x16x32_bf16 v[16:19], v[144:147], v[176:179], 0
	v_mfma_f32_16x16x32_bf16 v[72:75], v[136:139], v[184:187], 0
	v_mfma_f32_16x16x32_bf16 v[8:11], v[144:147], v[184:187], 0
	v_mfma_f32_16x16x32_bf16 v[64:67], v[136:139], v[212:215], 0
	v_mfma_f32_16x16x32_bf16 v[0:3], v[144:147], v[212:215], 0
	v_mfma_f32_16x16x32_bf16 v[88:91], v[140:143], v[172:175], v[88:91]
	v_mfma_f32_16x16x32_bf16 v[24:27], v[148:151], v[172:175], v[24:27]
	v_mfma_f32_16x16x32_bf16 v[80:83], v[140:143], v[180:183], v[80:83]
	v_mfma_f32_16x16x32_bf16 v[16:19], v[148:151], v[180:183], v[16:19]
	v_mfma_f32_16x16x32_bf16 v[72:75], v[140:143], v[208:211], v[72:75]
	v_mfma_f32_16x16x32_bf16 v[8:11], v[148:151], v[208:211], v[8:11]
	v_mfma_f32_16x16x32_bf16 v[64:67], v[140:143], v[216:219], v[64:67]
	v_mfma_f32_16x16x32_bf16 v[0:3], v[148:151], v[216:219], v[0:3]
	s_setprio 0
	s_barrier
	s_add_i32 s52, 0, 0x18000
	s_add_i32 s53, 0, 0x1c000
	v_add_u32_e32 v132, s52, v196
	v_add_u32_e32 v148, s53, v196
	ds_read_b128 v[120:123], v132
	ds_read_b128 v[124:127], v132 offset:1024
	ds_read_b128 v[128:131], v132 offset:2048
	ds_read_b128 v[132:135], v132 offset:3072
	ds_read_b128 v[136:139], v148
	ds_read_b128 v[140:143], v148 offset:1024
	ds_read_b128 v[144:147], v148 offset:2048
	ds_read_b128 v[148:151], v148 offset:3072
	s_add_u32 s34, s34, 0x80000
	s_addc_u32 s35, s35, 0
	s_mov_b32 m0, s39
	v_lshl_add_u64 v[228:229], s[34:35], 0, v[190:191]
	ds_read_b128 v[168:171], v207 offset:32768
	ds_read_b128 v[172:175], v207 offset:33792
	ds_read_b128 v[176:179], v207 offset:34816
	ds_read_b128 v[180:183], v207 offset:35840
	ds_read_b128 v[184:187], v207 offset:36864
	ds_read_b128 v[208:211], v207 offset:37888
	ds_read_b128 v[212:215], v207 offset:38912
	ds_read_b128 v[216:219], v207 offset:39936
	global_load_lds_dwordx4 v[228:229], off
	v_lshl_add_u64 v[228:229], s[34:35], 0, v[192:193]
	s_mov_b32 m0, s40
	s_nop 0
	global_load_lds_dwordx4 v[228:229], off
	s_waitcnt vmcnt(8)
	s_waitcnt lgkmcnt(0)
	s_barrier
	s_setprio 1
	s_waitcnt lgkmcnt(0)
	v_mfma_f32_16x16x32_bf16 v[156:159], v[120:123], v[168:171], v[156:159]
	v_mfma_f32_16x16x32_bf16 v[60:63], v[128:131], v[168:171], v[60:63]
	v_mfma_f32_16x16x32_bf16 v[116:119], v[120:123], v[176:179], v[116:119]
	v_mfma_f32_16x16x32_bf16 v[52:55], v[128:131], v[176:179], v[52:55]
	v_mfma_f32_16x16x32_bf16 v[108:111], v[120:123], v[184:187], v[108:111]
	v_mfma_f32_16x16x32_bf16 v[44:47], v[128:131], v[184:187], v[44:47]
	v_mfma_f32_16x16x32_bf16 v[100:103], v[120:123], v[212:215], v[100:103]
	v_mfma_f32_16x16x32_bf16 v[36:39], v[128:131], v[212:215], v[36:39]
	v_mfma_f32_16x16x32_bf16 v[156:159], v[124:127], v[172:175], v[156:159]
	v_mfma_f32_16x16x32_bf16 v[60:63], v[132:135], v[172:175], v[60:63]
	v_mfma_f32_16x16x32_bf16 v[116:119], v[124:127], v[180:183], v[116:119]
	v_mfma_f32_16x16x32_bf16 v[52:55], v[132:135], v[180:183], v[52:55]
	v_mfma_f32_16x16x32_bf16 v[108:111], v[124:127], v[208:211], v[108:111]
	v_mfma_f32_16x16x32_bf16 v[44:47], v[132:135], v[208:211], v[44:47]
	v_mfma_f32_16x16x32_bf16 v[100:103], v[124:127], v[216:219], v[100:103]
	v_mfma_f32_16x16x32_bf16 v[36:39], v[132:135], v[216:219], v[36:39]
	s_setprio 0
	s_setprio 1
	v_mfma_f32_16x16x32_bf16 v[152:155], v[136:139], v[168:171], v[152:155]
	v_mfma_f32_16x16x32_bf16 v[56:59], v[144:147], v[168:171], v[56:59]
	v_mfma_f32_16x16x32_bf16 v[112:115], v[136:139], v[176:179], v[112:115]
	v_mfma_f32_16x16x32_bf16 v[48:51], v[144:147], v[176:179], v[48:51]
	v_mfma_f32_16x16x32_bf16 v[104:107], v[136:139], v[184:187], v[104:107]
	v_mfma_f32_16x16x32_bf16 v[40:43], v[144:147], v[184:187], v[40:43]
	v_mfma_f32_16x16x32_bf16 v[96:99], v[136:139], v[212:215], v[96:99]
	v_mfma_f32_16x16x32_bf16 v[32:35], v[144:147], v[212:215], v[32:35]
	v_mfma_f32_16x16x32_bf16 v[152:155], v[140:143], v[172:175], v[152:155]
	v_mfma_f32_16x16x32_bf16 v[56:59], v[148:151], v[172:175], v[56:59]
	v_mfma_f32_16x16x32_bf16 v[112:115], v[140:143], v[180:183], v[112:115]
	v_mfma_f32_16x16x32_bf16 v[48:51], v[148:151], v[180:183], v[48:51]
	v_mfma_f32_16x16x32_bf16 v[104:107], v[140:143], v[208:211], v[104:107]
	v_mfma_f32_16x16x32_bf16 v[40:43], v[148:151], v[208:211], v[40:43]
	v_mfma_f32_16x16x32_bf16 v[96:99], v[140:143], v[216:219], v[96:99]
	v_mfma_f32_16x16x32_bf16 v[32:35], v[148:151], v[216:219], v[32:35]
	s_setprio 0
	s_barrier
; #define PG8_STAGE(bufoff, gbase, voff) do { _Pragma("unroll") for (int _i = 0; _i < 2; ++_i) \
;         __builtin_amdgcn_global_load_lds((const unsigned*)((const char*)(gbase) + (voff)[_i]), (LAS unsigned*)(lds + (bufoff) + ldsw + _i * 8192), 16, 0, 0); } while (0)
; #define PG8_LDA(dst, b, h) do { _Pragma("unroll") for (int m = 0; m < 4; ++m) _Pragma("unroll") for (int k = 0; k < 2; ++k) dst[m][k] = *(const LAS bf16x8*)(lds + PG8_SA(b, h) + aoff + m * 2048 + k * 1024); } while (0)
; #define PG8_MMA(ai, bj, At, Bt) do { __builtin_amdgcn_s_setprio(1); _Pragma("unroll") for (int m = 0; m < 4; ++m) _Pragma("unroll") for (int n = 0; n < 2; ++n) _Pragma("unroll") for (int k = 0; k < 2; ++k) \
;         acc[ai][bj][m][n] = __builtin_amdgcn_mfma_f32_16x16x32_bf16(Bt[n][k], At[m][k], acc[ai][bj][m][n], 0, 0, 0); __builtin_amdgcn_s_setprio(0); } while (0)
; #define PG8_WAIT_V(n) asm volatile("s_waitcnt vmcnt(" #n ")" ::: "memory")
; #define PG8_WAIT_L(n) asm volatile("s_waitcnt lgkmcnt(" #n ")" ::: "memory")
; #define PG8_BAR __builtin_amdgcn_s_barrier()
; #define PG8_SCHED __builtin_amdgcn_sched_barrier(0)
; template <class Epi, class Sched, bool DEFER>
; __device__ __forceinline__ void gemm_fast_core(LAS unsigned char* lds, const GemmP g, const Sched& S, const Epi& E, f32x4 (&acc)[2][2][4][2], Unit& cur) {
;     ...
;         for (int t = 0; t < nt; t += 2) {
;     ...
;             PG8_LDA(At, 1, 1); PG8_STAGE(PG8_SB(1, 0), b3, voffB); PG8_STAGE(PG8_SB(1, 1), b3 + hstepB, voffB); PG8_STAGE(PG8_SA(1, 0), a3, voffA);
;             PG8_WAIT_V(8); PG8_WAIT_L(0); PG8_BAR; PG8_MMA(1, 0, At, B0); PG8_MMA(1, 1, At, B1); PG8_BAR; PG8_SCHED;
	s_add_i32 s34, s52, s36
	v_lshl_add_u64 v[220:221], v[220:221], 0, s[8:9]
	s_mov_b32 m0, s34
	ds_read_b128 v[168:171], v207 offset:49152
	ds_read_b128 v[172:175], v207 offset:50176
	ds_read_b128 v[176:179], v207 offset:51200
	ds_read_b128 v[180:183], v207 offset:52224
	ds_read_b128 v[184:187], v207 offset:53248
	ds_read_b128 v[208:211], v207 offset:54272
	ds_read_b128 v[212:215], v207 offset:55296
	ds_read_b128 v[216:219], v207 offset:56320
	global_load_lds_dwordx4 v[220:221], off
	s_add_i32 m0, s34, 0x2000
	s_add_u32 s30, s30, 0x80080
	v_lshl_add_u64 v[220:221], v[222:223], 0, s[8:9]
	s_addc_u32 s31, s31, 0
	s_add_i32 s34, s53, s36
	global_load_lds_dwordx4 v[220:221], off
	v_lshl_add_u64 v[220:221], s[30:31], 0, v[162:163]
	s_mov_b32 m0, s34
	s_nop 0
	global_load_lds_dwordx4 v[220:221], off
	v_lshl_add_u64 v[220:221], s[30:31], 0, v[160:161]
	s_add_i32 m0, s34, 0x2000
	s_nop 0
	global_load_lds_dwordx4 v[220:221], off
	v_lshl_add_u64 v[220:221], v[224:225], 0, s[8:9]
	s_mov_b32 m0, s42
	s_nop 0
	global_load_lds_dwordx4 v[220:221], off
	v_lshl_add_u64 v[220:221], v[226:227], 0, s[8:9]
	s_mov_b32 m0, s43
	s_nop 0
	global_load_lds_dwordx4 v[220:221], off
	s_waitcnt vmcnt(8)
	s_waitcnt lgkmcnt(0)
	s_barrier
	s_setprio 1
	s_waitcnt lgkmcnt(0)
	v_mfma_f32_16x16x32_bf16 v[92:95], v[120:123], v[168:171], v[92:95]
	v_mfma_f32_16x16x32_bf16 v[28:31], v[128:131], v[168:171], v[28:31]
	v_mfma_f32_16x16x32_bf16 v[84:87], v[120:123], v[176:179], v[84:87]
	v_mfma_f32_16x16x32_bf16 v[20:23], v[128:131], v[176:179], v[20:23]
	v_mfma_f32_16x16x32_bf16 v[76:79], v[120:123], v[184:187], v[76:79]
	v_mfma_f32_16x16x32_bf16 v[12:15], v[128:131], v[184:187], v[12:15]
	v_mfma_f32_16x16x32_bf16 v[68:71], v[120:123], v[212:215], v[68:71]
	v_mfma_f32_16x16x32_bf16 v[4:7], v[128:131], v[212:215], v[4:7]
	v_mfma_f32_16x16x32_bf16 v[92:95], v[124:127], v[172:175], v[92:95]
	v_mfma_f32_16x16x32_bf16 v[28:31], v[132:135], v[172:175], v[28:31]
	v_mfma_f32_16x16x32_bf16 v[84:87], v[124:127], v[180:183], v[84:87]
	v_mfma_f32_16x16x32_bf16 v[20:23], v[132:135], v[180:183], v[20:23]
	v_mfma_f32_16x16x32_bf16 v[76:79], v[124:127], v[208:211], v[76:79]
	v_mfma_f32_16x16x32_bf16 v[12:15], v[132:135], v[208:211], v[12:15]
	v_mfma_f32_16x16x32_bf16 v[68:71], v[124:127], v[216:219], v[68:71]
	v_mfma_f32_16x16x32_bf16 v[4:7], v[132:135], v[216:219], v[4:7]
	s_setprio 0
	s_setprio 1
	v_mfma_f32_16x16x32_bf16 v[88:91], v[136:139], v[168:171], v[88:91]
	v_mfma_f32_16x16x32_bf16 v[24:27], v[144:147], v[168:171], v[24:27]
	v_mfma_f32_16x16x32_bf16 v[80:83], v[136:139], v[176:179], v[80:83]
	v_mfma_f32_16x16x32_bf16 v[16:19], v[144:147], v[176:179], v[16:19]
	v_mfma_f32_16x16x32_bf16 v[72:75], v[136:139], v[184:187], v[72:75]
	v_mfma_f32_16x16x32_bf16 v[8:11], v[144:147], v[184:187], v[8:11]
	v_mfma_f32_16x16x32_bf16 v[64:67], v[136:139], v[212:215], v[64:67]
	v_mfma_f32_16x16x32_bf16 v[0:3], v[144:147], v[212:215], v[0:3]
	v_mfma_f32_16x16x32_bf16 v[88:91], v[140:143], v[172:175], v[88:91]
	v_mfma_f32_16x16x32_bf16 v[24:27], v[148:151], v[172:175], v[24:27]
	v_mfma_f32_16x16x32_bf16 v[80:83], v[140:143], v[180:183], v[80:83]
	v_mfma_f32_16x16x32_bf16 v[16:19], v[148:151], v[180:183], v[16:19]
	v_mfma_f32_16x16x32_bf16 v[72:75], v[140:143], v[208:211], v[72:75]
	v_mfma_f32_16x16x32_bf16 v[8:11], v[148:151], v[208:211], v[8:11]
	v_mfma_f32_16x16x32_bf16 v[64:67], v[140:143], v[216:219], v[64:67]
	v_mfma_f32_16x16x32_bf16 v[0:3], v[148:151], v[216:219], v[0:3]
	s_setprio 0
	s_barrier
	s_add_i32 s51, s51, 2
	s_add_u32 s28, s28, 0x100
	s_addc_u32 s29, s29, 0
	s_add_u32 s49, s49, 0x100
	s_addc_u32 s50, s50, 0
	s_cmp_gt_u32 s51, 29
	s_cbranch_scc0 .LBB0_1799
	s_branch .Lpeel_p9_done
	.p2align 6
